# l0_prep statistics loop: k-rope loads issued at the top of the iteration with the row loads; waits no longer drain the previous stores
# speedup vs baseline: 1.0061x; 1.0046x over previous
; DI unsigned pk2(float lo, float hi) { f32x2 v = {lo, hi}; bf16x2_t b = __builtin_convertvector(v, bf16x2_t); return __builtin_bit_cast(unsigned, b); }
; DI float bf2f(bf16_t b) { return __uint_as_float(((unsigned)b) << 16); }
; DI float bflo(unsigned u) { return __uint_as_float(u << 16); }
; DI float bfhi(unsigned u) { return __uint_as_float(u & 0xffff0000u); }
; DI void phase_l0_prep(int wv, const ArgP a) {
;     ...
;     for (int t = blockIdx.x * 8 + wave; t < S; t += gridDim.x * 8) {
;         const bf16_t* zr = Z + (size_t)t * 1536;
;         float sq = 0.f, skv = 0.f;
;         { const u32x2 v = *(const u32x2*)(zr + 1024 + lane * 4); const float p0 = bflo(v.x), p1 = bfhi(v.x), p2 = bflo(v.y), p3 = bfhi(v.y); sq = p0 * p0 + p1 * p1 + p2 * p2 + p3 * p3; }
;         { const unsigned v = *(const unsigned*)(zr + 1280 + lane * 2); const float p0 = bflo(v), p1 = bfhi(v); skv = p0 * p0 + p1 * p1; }
;         sq = wave_sum(sq); skv = wave_sum(skv);
;         if (lane == 0) { rsq[t] = rsqrtf(sq * (1.f / 256.f) + EPS); rskv[t] = rsqrtf(skv * (1.f / 128.f) + EPS); }
;         if (lane < 16) { const float x1 = bf2f(zr[1408 + lane]), x2 = bf2f(zr[1424 + lane]); const float c = cst[(size_t)t * 32 + 2 * lane], s = cst[(size_t)t * 32 + 2 * lane + 1];
;             const unsigned w = pk2(x1 * c - x2 * s, x2 * c + x1 * s);
; #pragma unroll
;             for (int h = 0; h < 8; ++h) *(unsigned*)(KB + ((size_t)h * S + t) * 96 + 64 + 2 * lane) = w; }
;     }
.LBB0_465:
	v_mad_i64_i32 v[16:17], s[8:9], v0, s21, v[6:7]
	v_lshl_add_u64 v[18:19], v[16:17], 0, v[8:9]
	global_load_dwordx2 v[18:19], v[18:19], off offset:2048
	s_waitcnt lgkmcnt(0)
	v_lshl_add_u64 v[20:21], v[16:17], 0, v[12:13]
	global_load_dword v1, v[20:21], off offset:2560
	v_mov_b32_e32 v44, v0
	v_ashrrev_i32_e32 v45, 31, v0
	v_lshl_add_u64 v[46:47], v[16:17], 0, v[2:3]
	v_lshlrev_b64 v[44:45], 7, v[44:45]
	v_lshl_add_u64 v[44:45], v[4:5], 0, v[44:45]
	s_and_saveexec_b64 s[18:19], s[6:7]
	global_load_ushort v40, v[46:47], off offset:2816
	global_load_ushort v41, v[46:47], off offset:2848
	global_load_dwordx2 v[42:43], v[44:45], off
	s_or_b64 exec, exec, s[18:19]
	s_waitcnt vmcnt(4)
	v_and_b32_e32 v11, 0xffff0000, v18
	v_and_b32_e32 v21, 0xffff0000, v19
	v_lshlrev_b32_e32 v19, 16, v19
	v_lshlrev_b32_e32 v18, 16, v18
	s_waitcnt vmcnt(3)
	v_lshlrev_b32_e32 v20, 16, v1
	v_and_b32_e32 v1, 0xffff0000, v1
	v_pk_mul_f32 v[18:19], v[18:19], v[18:19]
	v_mul_f32_e32 v22, v1, v1
	v_fma_f32 v1, v11, v11, v18
	v_add_f32_e32 v23, v19, v1
	v_pk_fma_f32 v[18:19], v[20:21], v[20:21], v[22:23]
	ds_bpermute_b32 v21, v193, v19
	ds_bpermute_b32 v20, v193, v18
	v_ashrrev_i32_e32 v1, 31, v0
	s_waitcnt lgkmcnt(0)
	v_pk_add_f32 v[18:19], v[18:19], v[20:21]
	ds_bpermute_b32 v21, v194, v19
	ds_bpermute_b32 v20, v194, v18
	s_waitcnt lgkmcnt(0)
	v_pk_add_f32 v[18:19], v[18:19], v[20:21]
	ds_bpermute_b32 v21, v197, v19
	ds_bpermute_b32 v20, v197, v18
	s_waitcnt lgkmcnt(0)
	v_pk_add_f32 v[18:19], v[18:19], v[20:21]
	ds_bpermute_b32 v21, v198, v19
	ds_bpermute_b32 v20, v198, v18
	s_waitcnt lgkmcnt(0)
	v_pk_add_f32 v[18:19], v[18:19], v[20:21]
	ds_bpermute_b32 v21, v199, v19
	ds_bpermute_b32 v20, v199, v18
	s_waitcnt lgkmcnt(0)
	v_pk_add_f32 v[18:19], v[18:19], v[20:21]
	ds_bpermute_b32 v21, v195, v19
	ds_bpermute_b32 v20, v195, v18
	s_and_saveexec_b64 s[18:19], s[4:5]
	s_cbranch_execz .LBB0_467
	s_waitcnt lgkmcnt(0)
	v_pk_add_f32 v[18:19], v[18:19], v[20:21]
	v_lshlrev_b64 v[22:23], 2, v[0:1]
	v_pk_fma_f32 v[18:19], v[18:19], s[2:3], v[14:15] op_sel_hi:[1,1,0]
	v_lshl_add_u64 v[24:25], s[12:13], 0, v[22:23]
	v_mul_f32_e32 v11, 0x4b800000, v19
	v_cmp_gt_f32_e32 vcc, s22, v19
	v_mul_f32_e32 v15, 0x4b800000, v18
	v_cmp_gt_f32_e64 s[8:9], s22, v18
	v_cndmask_b32_e32 v11, v19, v11, vcc
	v_rsq_f32_e32 v11, v11
	v_cndmask_b32_e64 v15, v18, v15, s[8:9]
	v_rsq_f32_e32 v15, v15
	v_mul_f32_e32 v18, 0x45800000, v11
	v_cndmask_b32_e32 v11, v11, v18, vcc
	global_store_dword v[24:25], v11, off
	v_mul_f32_e32 v11, 0x45800000, v15
	v_cndmask_b32_e64 v11, v15, v11, s[8:9]
	v_lshl_add_u64 v[18:19], s[14:15], 0, v[22:23]
	global_store_dword v[18:19], v11, off
.LBB0_467:
	s_or_b64 exec, exec, s[18:19]
	s_and_saveexec_b64 s[8:9], s[6:7]
	s_cbranch_execz .LBB0_464
	s_waitcnt lgkmcnt(0)
	v_mov_b64_e32 v[16:17], s[0:1]
	v_mov_b32_e32 v11, v3
	v_mad_i64_i32 v[16:17], s[18:19], v0, s23, v[16:17]
	v_lshl_add_u64 v[16:17], v[16:17], 0, v[10:11]
	v_add_co_u32_e32 v18, vcc, s24, v16
	s_waitcnt vmcnt(4)
	v_lshlrev_b32_e32 v34, 16, v40
	v_addc_co_u32_e32 v19, vcc, 0, v17, vcc
	v_add_co_u32_e32 v22, vcc, s25, v16
	s_waitcnt vmcnt(3)
	v_lshlrev_b32_e32 v36, 16, v41
	v_addc_co_u32_e32 v23, vcc, 0, v17, vcc
	v_add_co_u32_e32 v24, vcc, s26, v16
	s_waitcnt vmcnt(2)
	v_pk_mul_f32 v[36:37], v[42:43], v[36:37] op_sel:[1,0] op_sel_hi:[0,0]
	v_addc_co_u32_e32 v25, vcc, 0, v17, vcc
	v_add_co_u32_e32 v26, vcc, s27, v16
	v_pk_fma_f32 v[38:39], v[42:43], v[34:35], v[36:37] neg_lo:[0,0,1] neg_hi:[0,0,1]
	s_nop 0
	v_addc_co_u32_e32 v27, vcc, 0, v17, vcc
	v_add_co_u32_e32 v28, vcc, 0xb96b000, v16
	v_pk_fma_f32 v[20:21], v[42:43], v[34:35], v[36:37] op_sel_hi:[1,0,1]
	s_nop 0
	v_addc_co_u32_e32 v29, vcc, 0, v17, vcc
	v_add_co_u32_e32 v30, vcc, 0xbc6b000, v16
	v_cvt_pk_bf16_f32 v1, v38, v21
	s_nop 0
	v_addc_co_u32_e32 v31, vcc, 0, v17, vcc
	v_add_co_u32_e32 v32, vcc, 0xbf6b000, v16
	s_nop 1
	v_addc_co_u32_e32 v33, vcc, 0, v17, vcc
	v_add_co_u32_e32 v16, vcc, 0xc26b000, v16
	s_nop 1
	v_addc_co_u32_e32 v17, vcc, 0, v17, vcc
	global_store_dword v[18:19], v1, off offset:128
	global_store_dword v[22:23], v1, off offset:128
	global_store_dword v[24:25], v1, off offset:128
	global_store_dword v[26:27], v1, off offset:128
	global_store_dword v[28:29], v1, off offset:128
	global_store_dword v[30:31], v1, off offset:128
	global_store_dword v[32:33], v1, off offset:128
	global_store_dword v[16:17], v1, off offset:128
	s_branch .LBB0_464
